# attention chunk loop: K/V chunk loads issued two chunks ahead of their LDS store (second register set by chunk parity, vmcnt 4 at the store)
# baseline (speedup 1.0000x reference)
.Laddr478_b:
	s_or_saveexec_b64 s[72:73], s[72:73]
	v_mov_b64_e32 v[40:41], s[90:91]
	s_xor_b64 exec, exec, s[72:73]
	v_ashrrev_i32_e32 v39, 31, v38
	v_lshlrev_b64 v[34:35], 7, v[38:39]
	v_lshl_add_u64 v[34:35], v[156:157], 0, v[34:35]
	v_ashrrev_i32_e32 v37, 31, v36
	v_mov_b64_e32 v[40:41], v[158:159]
	s_or_b64 exec, exec, s[72:73]
	v_lshlrev_b64 v[36:37], 13, v[36:37]
	v_lshl_add_u64 v[36:37], v[40:41], 0, v[36:37]
	v_cndmask_b32_e64 v250, v242, v34, s[0:1]
	v_cndmask_b32_e64 v251, v243, v35, s[0:1]
	v_cndmask_b32_e64 v252, v248, v36, s[0:1]
	v_cndmask_b32_e64 v253, v249, v37, s[0:1]
	s_mov_b64 s[98:99], 0x800
	v_lshl_add_u64 v[254:255], v[132:133], 0, v[138:139]
	v_lshl_add_u64 v[254:255], v[254:255], 0, s[98:99]
	v_lshl_add_u64 v[242:243], v[242:243], 0, v[254:255]
	v_lshl_add_u64 v[248:249], v[248:249], 0, v[254:255]
	v_lshl_add_u64 v[250:251], v[250:251], 0, v[254:255]
	v_lshl_add_u64 v[252:253], v[252:253], 0, v[254:255]
	v_readfirstlane_b32 s100, v183
	s_movk_i32 s98, 2
	s_add_i32 s99, s100, -1
	s_min_u32 s98, s98, s99
	s_cmp_lt_u32 s100, 9
	s_cbranch_scc1 .Lg_r2p
	s_cmp_lt_u32 s98, 8
	s_cbranch_scc1 .Lg_r1p
	s_sub_u32 s98, s98, 8

.Lg_ldp:
	global_load_dwordx4 v[238:241], v[34:35], off offset:-2048
	global_load_dwordx4 v[234:237], v[34:35], off offset:2048
	global_load_dwordx4 v[230:233], v[36:37], off offset:-2048
	global_load_dwordx4 v[226:229], v[36:37], off offset:2048
	s_branch .LBB0_476

.LBB0_476:
	s_add_i32 s79, s3, 1
	s_bitcmp1_b32 s79, 0
	s_cselect_b32 s72, 0x4800, 0
	v_add_u32_e32 v34, s72, v160
	v_add_u32_e32 v35, v34, v168
	v_add_u32_e32 v36, v35, v169
	v_add_u32_e32 v34, v34, v170
	s_waitcnt lgkmcnt(0)
	s_barrier
	s_waitcnt vmcnt(4)
	s_bitcmp1_b32 s79, 0
	s_cbranch_scc0 .Lat2_sB
	ds_write_b128 v36, v[126:129]
	v_add_u32_e32 v36, v34, v169
	ds_write_b128 v36, v[122:125]
	v_add_u32_e32 v35, v35, v167
	v_add_u32_e32 v34, v34, v167
	v_add_u32_e32 v35, 0x2000, v35
	v_add_u32_e32 v34, 0x2000, v34
	ds_write2_b64 v35, v[118:119], v[120:121] offset0:128 offset1:130
	ds_write2_b64 v34, v[114:115], v[116:117] offset0:128 offset1:130
	s_branch .Lat2_sd
.Lat2_sB:
	ds_write_b128 v36, v[238:241]
	v_add_u32_e32 v36, v34, v169
	ds_write_b128 v36, v[234:237]
	v_add_u32_e32 v35, v35, v167
	v_add_u32_e32 v34, v34, v167
	v_add_u32_e32 v35, 0x2000, v35
	v_add_u32_e32 v34, 0x2000, v34
	ds_write2_b64 v35, v[230:231], v[232:233] offset0:128 offset1:130
	ds_write2_b64 v34, v[226:227], v[228:229] offset0:128 offset1:130
.Lat2_sd:
	s_add_i32 s98, s79, 2
	s_add_i32 s99, s100, -1
	s_min_u32 s98, s98, s99
	s_cmp_lt_u32 s100, 9
	s_cbranch_scc1 .Lg_r2
	s_cmp_lt_u32 s98, 8
	s_cbranch_scc1 .Lg_r1
	s_sub_u32 s98, s98, 8

.Lg_ld:
	s_bitcmp1_b32 s79, 0
	s_cbranch_scc0 .Lat2_lB
	global_load_dwordx4 v[126:129], v[34:35], off offset:-2048
	global_load_dwordx4 v[122:125], v[34:35], off offset:2048
	global_load_dwordx4 v[118:121], v[36:37], off offset:-2048
	global_load_dwordx4 v[114:117], v[36:37], off offset:2048
	s_branch .Lat2_ld
.Lat2_lB:
	global_load_dwordx4 v[238:241], v[34:35], off offset:-2048
	global_load_dwordx4 v[234:237], v[34:35], off offset:2048
	global_load_dwordx4 v[230:233], v[36:37], off offset:-2048
	global_load_dwordx4 v[226:229], v[36:37], off offset:2048
.Lat2_ld:
	s_cmp_gt_u32 s3, 7
	s_cselect_b64 s[72:73], -1, 0
	s_and_b64 s[94:95], s[0:1], s[72:73]
	v_mov_b32_e32 v66, 0
	s_mov_b64 vcc, -1
	s_and_saveexec_b64 s[76:77], s[94:95]
	v_add_u32_e32 v34, s3, v189
	v_cmp_ge_i32_e32 vcc, v34, v182
	v_cmp_lt_i32_e64 s[72:73], v34, v186
	s_and_b64 s[72:73], vcc, s[72:73]
	s_orn2_b64 vcc, s[72:73], exec
	v_mov_b32_e32 v66, v188
	s_or_b64 exec, exec, s[76:77]
	s_and_saveexec_b64 s[72:73], vcc
	s_cbranch_execz .LBB0_475
	s_bitcmp1_b32 s3, 0
	s_cselect_b32 s3, 0x4800, 0
	v_add_u32_e32 v137, s3, v173
	ds_read_b128 v[192:195], v137
	ds_read_b128 v[208:211], v137 offset:4608
	ds_read_b128 v[196:199], v137 offset:32
	ds_read_b128 v[214:217], v137 offset:4640
	ds_read_b128 v[200:203], v137 offset:64
	ds_read_b128 v[218:221], v137 offset:4672
	ds_read_b128 v[204:207], v137 offset:96
	ds_read_b128 v[222:225], v137 offset:4704
	s_waitcnt lgkmcnt(6)
	v_mfma_f32_32x32x16_bf16 v[50:65], v[192:195], v[98:101], 0
	v_mfma_f32_32x32x16_bf16 v[34:49], v[208:211], v[98:101], 0
	s_waitcnt lgkmcnt(4)
	v_mfma_f32_32x32x16_bf16 v[50:65], v[196:199], v[102:105], v[50:65]
	v_mfma_f32_32x32x16_bf16 v[34:49], v[214:217], v[102:105], v[34:49]
	s_waitcnt lgkmcnt(2)
	v_mfma_f32_32x32x16_bf16 v[50:65], v[200:203], v[106:109], v[50:65]
	v_mfma_f32_32x32x16_bf16 v[34:49], v[218:221], v[106:109], v[34:49]
	s_waitcnt lgkmcnt(0)
	v_mfma_f32_32x32x16_bf16 v[50:65], v[204:207], v[110:113], v[50:65]
	v_mfma_f32_32x32x16_bf16 v[34:49], v[222:225], v[110:113], v[34:49]
	ds_read_b128 v[192:195], v137 offset:9216
	ds_read_b128 v[208:211], v137 offset:13824
	ds_read_b128 v[196:199], v137 offset:9248
	ds_read_b128 v[214:217], v137 offset:13856
	ds_read_b128 v[200:203], v137 offset:9280
	ds_read_b128 v[218:221], v137 offset:13888
	ds_read_b128 v[204:207], v137 offset:9312
	ds_read_b128 v[222:225], v137 offset:13920
	s_and_saveexec_b64 vcc, s[94:95]
	s_cbranch_execz .LBB0_549
	v_lshl_add_u32 v141, v66, 2, v187
	v_add_u32_e32 v141, 0x903c, v141
	v_mov_b32_e32 v246, 0xff800000
	v_readfirstlane_b32 s98, v212
	s_nop 0
	s_bitcmp1_b32 s98, 6
	s_cbranch_scc1 .Lwin_odd
	s_branch .Lwin_even

.LBB0_551:
	s_waitcnt vmcnt(0)
	v_readlane_b32 s0, v244, 4
	v_readlane_b32 s1, v244, 5
	s_or_b64 exec, exec, s[0:1]
	v_readlane_b32 s64, v245, 62
	v_readlane_b32 s80, v245, 0
	v_readlane_b32 s62, v244, 2
	v_readlane_b32 s67, v244, 1
	v_readlane_b32 s68, v245, 60
	v_readlane_b32 s0, v245, 58
	v_readlane_b32 s70, v245, 56
	v_readlane_b32 s60, v245, 54
	v_readlane_b32 s92, v245, 12
	v_readlane_b32 s24, v245, 52
	v_readlane_b32 s52, v245, 50
	v_readlane_b32 s63, v244, 3
	v_readlane_b32 s65, v245, 63
	v_readlane_b32 s66, v244, 0
	v_readlane_b32 s69, v245, 61
	v_readlane_b32 s67, v245, 59
	v_readlane_b32 s71, v245, 57
	v_readlane_b32 s61, v245, 55
	s_mov_b32 s92, s0
	v_readlane_b32 s25, v245, 53
	v_readlane_b32 s53, v245, 51
	v_readlane_b32 s81, v245, 1
	v_readlane_b32 s82, v245, 2
	v_readlane_b32 s83, v245, 3
	v_readlane_b32 s84, v245, 4
	v_readlane_b32 s85, v245, 5
	v_readlane_b32 s86, v245, 6
	v_readlane_b32 s87, v245, 7
	v_readlane_b32 s88, v245, 8
	v_readlane_b32 s89, v245, 9
	v_readlane_b32 s90, v245, 10
	v_readlane_b32 s91, v245, 11
	v_readlane_b32 s93, v245, 13
	v_readlane_b32 s94, v245, 14
	v_readlane_b32 s95, v245, 15
